# attention key loop rewritten by hand: LDS-DMA staged swizzled K/V tiles, 3-buffer ring, MFMA/exp/LDS interleaved per slot, scan fused
# speedup vs baseline: 1.0879x; 1.0879x over previous
.LBB0_427:
	s_add_i32 s0, s18, 32
	s_cmpk_gt_i32 s18, 0x5f
	s_mov_b32 s18, s0
	s_barrier
	s_cbranch_scc1 .LBB0_448
.LBB0_428:
	s_ashr_i32 s0, s18, 6
	s_add_i32 s4, s0, s19
	s_ashr_i32 s16, s4, 2
	v_mov_b32_e32 v132, v188
	s_ashr_i32 s17, s16, 31
	v_readfirstlane_b32 s34, v132
	s_lshl_b32 s5, s18, 7
	s_bfe_u32 s31, s34, 0x20006
	s_lshl_b64 s[2:3], s[16:17], 13
	s_and_b32 s0, s5, 0x1f80
	s_or_b32 s0, s2, s0
	s_lshl_b32 s2, s31, 5
	v_and_b32_e32 v202, 31, v132
	s_or_b32 s0, s0, s2
	v_or_b32_e32 v176, s0, v202
	v_mad_u64_u32 v[16:17], s[0:1], v176, s20, v[172:173]
	s_lshl_b32 s0, s4, 7
	s_ashr_i32 s30, s34, 8
	s_and_b32 s0, s0, 0x180
	v_mad_i32_i24 v17, s3, v189, v17
	s_lshl_b32 s12, s0, 1
	s_lshl_b32 s0, s30, 6
	v_bfe_u32 v133, v132, 5, 1
	v_lshl_add_u64 v[16:17], v[16:17], 0, s[12:13]
	s_ashr_i32 s1, s0, 31
	v_lshl_add_u64 v[16:17], s[0:1], 1, v[16:17]
	v_lshlrev_b32_e32 v166, 4, v133
	v_lshl_add_u64 v[16:17], v[16:17], 0, v[166:167]
	global_load_dwordx4 v[90:93], v[16:17], off offset:3136
	global_load_dwordx4 v[96:99], v[16:17], off offset:3168
	global_load_dwordx4 v[108:111], v[16:17], off offset:3072
	global_load_dwordx4 v[112:115], v[16:17], off offset:3104
	v_cmp_lt_i32_e32 vcc, v191, v192
	s_or_b32 s0, s2, s5
	s_lshl_b32 s0, s0, 1
	v_cndmask_b32_e32 v16, v190, v191, vcc
	v_lshlrev_b32_e32 v195, 2, v16
	v_and_b32_e32 v16, 32, v132
	global_load_dwordx4 v[40:43], v16, s[62:63] offset:144
	global_load_dwordx4 v[44:47], v16, s[62:63] offset:128
	global_load_dwordx4 v[28:31], v16, s[62:63] offset:208
	global_load_dwordx4 v[36:39], v16, s[62:63] offset:192
	global_load_dwordx4 v[72:75], v16, s[62:63] offset:16
	global_load_dwordx4 v[76:79], v16, s[62:63]
	global_load_dwordx4 v[64:67], v16, s[62:63] offset:80
	global_load_dwordx4 v[68:71], v16, s[62:63] offset:64
	v_lshlrev_b32_e32 v48, 6, v133
	v_and_or_b32 v16, s2, 32, v202
	s_and_b32 s0, s0, 0x3f80
	v_lshl_or_b32 v32, v16, 7, v48
	v_or_b32_e32 v60, s0, v48
	global_load_dwordx4 v[16:19], v32, s[10:11] offset:48
	global_load_dwordx4 v[20:23], v32, s[10:11] offset:32
	global_load_dwordx4 v[24:27], v32, s[10:11] offset:16
	s_nop 0
	global_load_dwordx4 v[32:35], v32, s[10:11]
	s_nop 0
	global_load_dwordx4 v[48:51], v60, s[10:11] offset:48
	global_load_dwordx4 v[52:55], v60, s[10:11] offset:32
	global_load_dwordx4 v[56:59], v60, s[10:11] offset:16
	s_nop 0
	global_load_dwordx4 v[60:63], v60, s[10:11]
	v_mov_b32_e32 v177, s3
	v_cmp_gt_i32_e32 vcc, s21, v132
	s_waitcnt vmcnt(19)
	v_lshlrev_b32_e32 v84, 16, v93
	s_waitcnt vmcnt(18)
	v_lshlrev_b32_e32 v80, 16, v99
	v_and_b32_e32 v81, 0xffff0000, v99
	v_lshlrev_b32_e32 v82, 16, v98
	v_and_b32_e32 v83, 0xffff0000, v98
	s_waitcnt vmcnt(17)
	v_lshlrev_b32_e32 v98, 16, v111
	v_and_b32_e32 v99, 0xffff0000, v111
	v_lshlrev_b32_e32 v102, 16, v110
	v_and_b32_e32 v103, 0xffff0000, v110
	v_lshlrev_b32_e32 v110, 16, v108
	v_and_b32_e32 v111, 0xffff0000, v108
	v_lshlrev_b32_e32 v106, 16, v109
	v_and_b32_e32 v107, 0xffff0000, v109
	v_pk_mul_f32 v[148:149], v[110:111], v[110:111]
	v_pk_mul_f32 v[144:145], v[106:107], v[106:107]
	v_add_f32_e32 v148, v148, v149
	v_add_f32_e32 v144, v144, v148
	v_pk_mul_f32 v[142:143], v[102:103], v[102:103]
	v_add_f32_e32 v144, v145, v144
	v_add_f32_e32 v142, v142, v144
	v_pk_mul_f32 v[138:139], v[98:99], v[98:99]
	v_add_f32_e32 v142, v143, v142
	s_waitcnt vmcnt(16)
	v_lshlrev_b32_e32 v108, 16, v112
	v_and_b32_e32 v109, 0xffff0000, v112
	v_add_f32_e32 v138, v138, v142
	v_lshlrev_b32_e32 v104, 16, v113
	v_and_b32_e32 v105, 0xffff0000, v113
	v_pk_mul_f32 v[112:113], v[108:109], v[108:109]
	v_add_f32_e32 v138, v139, v138
	v_add_f32_e32 v112, v112, v138
	v_pk_mul_f32 v[146:147], v[104:105], v[104:105]
	v_add_f32_e32 v112, v113, v112
	v_lshlrev_b32_e32 v100, 16, v114
	v_and_b32_e32 v101, 0xffff0000, v114
	v_add_f32_e32 v112, v146, v112
	v_and_b32_e32 v85, 0xffff0000, v93
	v_lshlrev_b32_e32 v88, 16, v92
	v_and_b32_e32 v89, 0xffff0000, v92
	v_lshlrev_b32_e32 v92, 16, v91
	v_and_b32_e32 v93, 0xffff0000, v91
	v_lshlrev_b32_e32 v86, 16, v97
	v_and_b32_e32 v87, 0xffff0000, v97
	v_lshlrev_b32_e32 v94, 16, v90
	v_and_b32_e32 v95, 0xffff0000, v90
	v_lshlrev_b32_e32 v90, 16, v96
	v_and_b32_e32 v91, 0xffff0000, v96
	v_lshlrev_b32_e32 v96, 16, v115
	v_and_b32_e32 v97, 0xffff0000, v115
	v_pk_mul_f32 v[114:115], v[100:101], v[100:101]
	v_add_f32_e32 v112, v147, v112
	v_add_f32_e32 v112, v114, v112
	v_pk_mul_f32 v[140:141], v[96:97], v[96:97]
	v_add_f32_e32 v112, v115, v112
	v_add_f32_e32 v112, v140, v112
	v_pk_mul_f32 v[134:135], v[94:95], v[94:95]
	v_add_f32_e32 v112, v141, v112
	v_add_f32_e32 v112, v134, v112
	v_pk_mul_f32 v[124:125], v[92:93], v[92:93]
	v_add_f32_e32 v112, v135, v112
	v_add_f32_e32 v112, v124, v112
	v_pk_mul_f32 v[120:121], v[88:89], v[88:89]
	v_add_f32_e32 v112, v125, v112
	v_add_f32_e32 v112, v120, v112
	v_pk_mul_f32 v[116:117], v[84:85], v[84:85]
	v_add_f32_e32 v112, v121, v112
	v_add_f32_e32 v112, v116, v112
	v_pk_mul_f32 v[136:137], v[90:91], v[90:91]
	v_add_f32_e32 v112, v117, v112
	v_add_f32_e32 v112, v136, v112
	v_pk_mul_f32 v[126:127], v[86:87], v[86:87]
	v_add_f32_e32 v112, v137, v112
	v_add_f32_e32 v112, v126, v112
	v_pk_mul_f32 v[122:123], v[82:83], v[82:83]
	v_add_f32_e32 v112, v127, v112
	v_add_f32_e32 v112, v122, v112
	v_pk_mul_f32 v[118:119], v[80:81], v[80:81]
	v_add_f32_e32 v112, v123, v112
	v_add_f32_e32 v112, v118, v112
	v_add_f32_e32 v134, v119, v112
	ds_bpermute_b32 v135, v195, v134
	v_lshrrev_b32_e32 v112, 6, v188
	v_lshrrev_b32_e32 v113, 4, v190
	v_and_b32_e32 v114, 15, v190
	v_lshl_add_u32 v115, v112, 3, v113
	v_mul_u32_u24_e32 v115, 0x1a00, v115
	v_and_b32_e32 v116, 1, v113
	v_and_b32_e32 v117, 2, v113
	v_lshl_or_b32 v116, v117, 2, v116
	v_xor_b32_e32 v116, v114, v116
	v_lshl_add_u32 v181, v116, 4, v115
	v_add_u32_e32 v165, 0x6800, v181
	v_lshlrev_b32_e32 v117, 2, v113
	v_xor_b32_e32 v117, v114, v117
	v_lshl_add_u32 v117, v117, 4, v115
	v_add_u32_e32 v207, 0x400, v117
	v_add_u32_e32 v208, 0x6c00, v117
	s_lshl_b32 s1, s16, 8
	s_add_i32 s1, s1, 0x8000
	s_mul_i32 s2, s1, 0x1a00
	s_add_u32 s22, s8, s12
	s_addc_u32 s23, s9, 0
	s_add_u32 s22, s22, 0x1000
	s_addc_u32 s23, s23, 0
	s_add_u32 s36, s22, s2
	s_addc_u32 s37, s23, 0
	s_lshl_b32 s3, s16, 13
	s_mul_i32 s3, s3, 0x1a00
	s_add_u32 s38, s22, s3
	s_addc_u32 s39, s23, 0
	s_lshr_b32 s17, s34, 6
	s_mul_i32 s17, s17, 0x840
	s_add_i32 m0, s17, 0
	s_nop 0
	global_load_lds_dwordx4 v181, s[36:37]
	s_add_i32 m0, s17, 1056
	s_nop 0
	global_load_lds_dwordx4 v165, s[36:37]
	s_add_i32 m0, s17, 16896
	s_nop 0
	global_load_lds_dwordx4 v207, s[36:37]
	s_add_i32 m0, s17, 17952
	s_nop 0
	global_load_lds_dwordx4 v208, s[36:37]
	s_add_u32 s36, s36, 0x68000
	s_addc_u32 s37, s37, 0
	s_add_i32 m0, s17, 33792
	s_nop 0
	global_load_lds_dwordx4 v181, s[36:37]
	s_add_i32 m0, s17, 34848
	s_nop 0
	global_load_lds_dwordx4 v165, s[36:37]
	s_add_i32 m0, s17, 50688
	s_nop 0
	global_load_lds_dwordx4 v207, s[36:37]
	s_add_i32 m0, s17, 51744
	s_nop 0
	global_load_lds_dwordx4 v208, s[36:37]
	s_add_u32 s36, s36, 0x68000
	s_addc_u32 s37, s37, 0
	v_and_b32_e32 v112, 31, v190
	v_lshrrev_b32_e32 v113, 5, v190
	v_lshrrev_b32_e32 v114, 8, v188
	v_lshl_or_b32 v113, v114, 3, v113
	v_and_b32_e32 v115, 3, v112
	v_and_b32_e32 v116, 1, v115
	v_and_b32_e32 v117, 2, v115
	v_lshl_or_b32 v116, v117, 2, v116
	v_xor_b32_e32 v116, v113, v116
	v_lshlrev_b32_e32 v116, 4, v116
	v_lshl_add_u32 v116, v115, 8, v116
	v_lshrrev_b32_e32 v117, 2, v112
	v_mul_u32_u24_e32 v117, 0x420, v117
	v_add_u32_e32 v178, v116, v117
	v_add_u32_e32 v180, 0x10800, v178
	v_and_b32_e32 v112, 3, v190
	v_bfe_u32 v113, v190, 2, 2
	v_bfe_u32 v114, v190, 4, 1
	v_lshrrev_b32_e32 v115, 5, v190
	v_mul_u32_u24_e32 v115, 0x420, v115
	v_lshl_add_u32 v115, v113, 8, v115
	v_lshl_add_u32 v115, v114, 5, v115
	v_lshl_add_u32 v115, v112, 3, v115
	v_add_u32_e32 v115, 0x4200, v115
	v_lshl_add_u32 v184, v113, 6, v115
	v_xor_b32_e32 v116, 1, v113
	v_lshl_add_u32 v185, v116, 6, v115
	v_xor_b32_e32 v116, 2, v113
	v_lshl_add_u32 v186, v116, 6, v115
	v_xor_b32_e32 v116, 3, v113
	v_lshl_add_u32 v187, v116, 6, v115
	v_add_u32_e32 v198, 0x10800, v184
	v_add_u32_e32 v199, 0x10800, v185
	v_add_u32_e32 v201, 0x10800, v186
	v_add_u32_e32 v203, 0x10800, v187
	v_mov_b32_e32 v128, 0
	v_mov_b32_e32 v129, 0
	v_mov_b32_e32 v130, 0
	v_mov_b32_e32 v131, 0
	v_lshlrev_b32_e32 v112, 4, v188
	v_add_u32_e32 v112, 0x14c00, v112
	ds_write_b128 v112, v[128:131]
	ds_write_b128 v112, v[128:131] offset:8192
	s_waitcnt vmcnt(8)
	s_waitcnt lgkmcnt(0)
	v_lshrrev_b32_e32 v136, 2, v132
	v_lshlrev_b32_e32 v179, 2, v133
	v_and_or_b32 v133, v136, 3, v179
	v_mul_u32_u24_e32 v204, 0x140, v133
	v_lshlrev_b32_e32 v133, 1, v132
	v_and_b32_e32 v205, 32, v133
	v_add_f32_e32 v133, v134, v135
	v_fmamk_f32 v133, v133, 0x3c800000, v193
	v_mul_f32_e32 v134, 0x4b800000, v133
	v_cmp_gt_f32_e32 vcc, s27, v133
	v_lshlrev_b32_e32 v132, 3, v132
	v_and_b32_e32 v206, 24, v132
	v_cndmask_b32_e32 v133, v133, v134, vcc
	v_rsq_f32_e32 v133, v133
	v_add3_u32 v197, v204, v205, v206
	v_add_u32_e32 v200, 0, v197
	s_lshl_b32 s0, s30, 7
	v_mul_f32_e32 v132, 0x45800000, v133
	v_cndmask_b32_e32 v132, v133, v132, vcc
	v_mul_f32_e32 v132, 0x3e38aa3b, v132
	v_pk_mul_f32 v[68:69], v[68:69], v[132:133] op_sel_hi:[1,0]
	v_pk_mul_f32 v[30:31], v[30:31], v[132:133] op_sel_hi:[1,0]
	v_pk_mul_f32 v[76:77], v[76:77], v[132:133] op_sel_hi:[1,0]
	v_pk_mul_f32 v[68:69], v[68:69], v[108:109]
	v_pk_mul_f32 v[30:31], v[30:31], v[80:81]
	v_mov_b32_e32 v80, v60
	v_mov_b32_e32 v81, v62
	v_mov_b32_e32 v62, v61
	v_pk_mul_f32 v[76:77], v[76:77], v[110:111]
	v_pk_mul_f32 v[70:71], v[70:71], v[132:133] op_sel_hi:[1,0]
	v_pk_mul_f32 v[60:61], v[62:63], v[68:69]
	v_pk_mul_f32 v[68:69], v[80:81], v[68:69]
	v_pk_mul_f32 v[78:79], v[78:79], v[132:133] op_sel_hi:[1,0]
	v_pk_mul_f32 v[70:71], v[70:71], v[104:105]
	v_pk_fma_f32 v[62:63], v[62:63], v[76:77], v[68:69]
	v_mov_b32_e32 v69, v58
	v_mov_b32_e32 v58, v57
	v_pk_mul_f32 v[78:79], v[78:79], v[106:107]
	v_mov_b32_e32 v68, v56
	v_pk_mul_f32 v[56:57], v[58:59], v[70:71]
	v_pk_mul_f32 v[64:65], v[64:65], v[132:133] op_sel_hi:[1,0]
	v_pk_fma_f32 v[56:57], v[68:69], v[78:79], v[56:57] neg_lo:[0,0,1] neg_hi:[0,0,1]
	v_pk_mul_f32 v[68:69], v[68:69], v[70:71]
	v_pk_mul_f32 v[72:73], v[72:73], v[132:133] op_sel_hi:[1,0]
	v_pk_mul_f32 v[64:65], v[64:65], v[100:101]
	v_pk_fma_f32 v[58:59], v[58:59], v[78:79], v[68:69]
	v_mov_b32_e32 v68, v52
	v_mov_b32_e32 v69, v54
	v_mov_b32_e32 v54, v53
	v_pk_mul_f32 v[72:73], v[72:73], v[102:103]
	v_pk_mul_f32 v[66:67], v[66:67], v[132:133] op_sel_hi:[1,0]
	v_pk_mul_f32 v[52:53], v[54:55], v[64:65]
	v_pk_mul_f32 v[64:65], v[68:69], v[64:65]
	v_pk_mul_f32 v[74:75], v[74:75], v[132:133] op_sel_hi:[1,0]
	v_pk_mul_f32 v[66:67], v[66:67], v[96:97]
	v_pk_fma_f32 v[54:55], v[54:55], v[72:73], v[64:65]
	v_mov_b32_e32 v65, v50
	v_mov_b32_e32 v50, v49
	v_pk_mul_f32 v[74:75], v[74:75], v[98:99]
	v_mov_b32_e32 v64, v48
	v_pk_mul_f32 v[48:49], v[50:51], v[66:67]
	v_pk_mul_f32 v[36:37], v[36:37], v[132:133] op_sel_hi:[1,0]
	v_pk_fma_f32 v[48:49], v[74:75], v[64:65], v[48:49] neg_lo:[0,0,1] neg_hi:[0,0,1]
	v_pk_mul_f32 v[64:65], v[64:65], v[66:67]
	v_pk_mul_f32 v[44:45], v[44:45], v[132:133] op_sel_hi:[1,0]
	v_pk_mul_f32 v[36:37], v[36:37], v[90:91]
	v_pk_fma_f32 v[50:51], v[50:51], v[74:75], v[64:65]
	v_mov_b32_e32 v64, v32
	v_mov_b32_e32 v65, v34
	v_mov_b32_e32 v34, v33
	v_pk_mul_f32 v[44:45], v[44:45], v[94:95]
	v_pk_mul_f32 v[38:39], v[38:39], v[132:133] op_sel_hi:[1,0]
	v_pk_mul_f32 v[32:33], v[36:37], v[34:35]
	v_pk_mul_f32 v[36:37], v[36:37], v[64:65]
	v_pk_mul_f32 v[46:47], v[46:47], v[132:133] op_sel_hi:[1,0]
	v_pk_mul_f32 v[38:39], v[38:39], v[86:87]
	v_pk_fma_f32 v[34:35], v[44:45], v[34:35], v[36:37]
	v_mov_b32_e32 v37, v26
	v_mov_b32_e32 v26, v25
	v_pk_mul_f32 v[46:47], v[46:47], v[92:93]
	v_mov_b32_e32 v36, v24
	v_pk_mul_f32 v[24:25], v[38:39], v[26:27]
	v_pk_mul_f32 v[28:29], v[28:29], v[132:133] op_sel_hi:[1,0]
	v_pk_fma_f32 v[24:25], v[46:47], v[36:37], v[24:25] neg_lo:[0,0,1] neg_hi:[0,0,1]
	v_pk_mul_f32 v[36:37], v[38:39], v[36:37]
	v_pk_mul_f32 v[40:41], v[40:41], v[132:133] op_sel_hi:[1,0]
	v_pk_mul_f32 v[28:29], v[28:29], v[82:83]
	v_pk_fma_f32 v[26:27], v[46:47], v[26:27], v[36:37]
	v_mov_b32_e32 v36, v20
	v_mov_b32_e32 v37, v22
	v_mov_b32_e32 v22, v21
	v_pk_mul_f32 v[40:41], v[40:41], v[88:89]
	v_pk_mul_f32 v[20:21], v[28:29], v[22:23]
	v_pk_mul_f32 v[28:29], v[28:29], v[36:37]
	v_pk_mul_f32 v[42:43], v[42:43], v[132:133] op_sel_hi:[1,0]
	v_pk_fma_f32 v[22:23], v[40:41], v[22:23], v[28:29]
	v_mov_b32_e32 v29, v18
	v_mov_b32_e32 v18, v17
	v_pk_mul_f32 v[42:43], v[42:43], v[84:85]
	v_mov_b32_e32 v28, v16
	v_pk_mul_f32 v[16:17], v[30:31], v[18:19]
	v_pk_fma_f32 v[60:61], v[80:81], v[76:77], v[60:61] neg_lo:[0,0,1] neg_hi:[0,0,1]
	v_pk_fma_f32 v[16:17], v[42:43], v[28:29], v[16:17] neg_lo:[0,0,1] neg_hi:[0,0,1]
	v_pk_mul_f32 v[28:29], v[30:31], v[28:29]
	v_pk_fma_f32 v[52:53], v[68:69], v[72:73], v[52:53] neg_lo:[0,0,1] neg_hi:[0,0,1]
	v_pk_fma_f32 v[32:33], v[44:45], v[64:65], v[32:33] neg_lo:[0,0,1] neg_hi:[0,0,1]
	v_pk_fma_f32 v[20:21], v[40:41], v[36:37], v[20:21] neg_lo:[0,0,1] neg_hi:[0,0,1]
	v_pk_fma_f32 v[18:19], v[42:43], v[18:19], v[28:29]
	v_cvt_pk_bf16_f32 v140, v60, v61
	v_cvt_pk_bf16_f32 v141, v56, v57
	v_cvt_pk_bf16_f32 v142, v52, v53
	v_cvt_pk_bf16_f32 v143, v48, v49
	v_cvt_pk_bf16_f32 v144, v62, v63
	v_cvt_pk_bf16_f32 v145, v58, v59
	v_cvt_pk_bf16_f32 v146, v54, v55
	v_cvt_pk_bf16_f32 v147, v50, v51
	v_cvt_pk_bf16_f32 v136, v32, v33
	v_cvt_pk_bf16_f32 v137, v24, v25
	v_cvt_pk_bf16_f32 v138, v20, v21
	v_cvt_pk_bf16_f32 v139, v16, v17
	v_cvt_pk_bf16_f32 v132, v34, v35
	v_cvt_pk_bf16_f32 v133, v26, v27
	v_cvt_pk_bf16_f32 v134, v22, v23
	v_cvt_pk_bf16_f32 v135, v18, v19
	v_mov_b32_e32 v64, 0
	v_mov_b32_e32 v65, 0
	v_mov_b32_e32 v66, 0
	v_mov_b32_e32 v67, 0
	v_mov_b32_e32 v68, 0
	v_mov_b32_e32 v69, 0
	v_mov_b32_e32 v70, 0
	v_mov_b32_e32 v71, 0
	v_mov_b32_e32 v72, 0
	v_mov_b32_e32 v73, 0
	v_mov_b32_e32 v74, 0
	v_mov_b32_e32 v75, 0
	v_mov_b32_e32 v76, 0
	v_mov_b32_e32 v77, 0
	v_mov_b32_e32 v78, 0
	v_mov_b32_e32 v79, 0
	v_mov_b32_e32 v48, 0
	v_mov_b32_e32 v49, 0
	v_mov_b32_e32 v50, 0
	v_mov_b32_e32 v51, 0
	v_mov_b32_e32 v52, 0
	v_mov_b32_e32 v53, 0
	v_mov_b32_e32 v54, 0
	v_mov_b32_e32 v55, 0
	v_mov_b32_e32 v56, 0
	v_mov_b32_e32 v57, 0
	v_mov_b32_e32 v58, 0
	v_mov_b32_e32 v59, 0
	v_mov_b32_e32 v60, 0
	v_mov_b32_e32 v61, 0
	v_mov_b32_e32 v62, 0
	v_mov_b32_e32 v63, 0
	v_mov_b32_e32 v32, 0
	v_mov_b32_e32 v33, 0
	v_mov_b32_e32 v34, 0
	v_mov_b32_e32 v35, 0
	v_mov_b32_e32 v36, 0
	v_mov_b32_e32 v37, 0
	v_mov_b32_e32 v38, 0
	v_mov_b32_e32 v39, 0
	v_mov_b32_e32 v40, 0
	v_mov_b32_e32 v41, 0
	v_mov_b32_e32 v42, 0
	v_mov_b32_e32 v43, 0
	v_mov_b32_e32 v44, 0
	v_mov_b32_e32 v45, 0
	v_mov_b32_e32 v46, 0
	v_mov_b32_e32 v47, 0
	v_mov_b32_e32 v16, 0
	v_mov_b32_e32 v17, 0
	v_mov_b32_e32 v18, 0
	v_mov_b32_e32 v19, 0
	v_mov_b32_e32 v20, 0
	v_mov_b32_e32 v21, 0
	v_mov_b32_e32 v22, 0
	v_mov_b32_e32 v23, 0
	v_mov_b32_e32 v24, 0
	v_mov_b32_e32 v25, 0
	v_mov_b32_e32 v26, 0
	v_mov_b32_e32 v27, 0
	v_mov_b32_e32 v28, 0
	v_mov_b32_e32 v29, 0
	v_mov_b32_e32 v30, 0
	v_mov_b32_e32 v31, 0
	v_mov_b32_e32 v80, 0xf149f2ca
	v_mov_b32_e32 v81, 0xf149f2ca
	v_mov_b32_e32 v82, 0xf149f2ca
	v_mov_b32_e32 v83, 0xf149f2ca
	v_mov_b32_e32 v84, 0xf149f2ca
	v_mov_b32_e32 v85, 0xf149f2ca
	v_mov_b32_e32 v86, 0xf149f2ca
	v_mov_b32_e32 v87, 0xf149f2ca
	v_mov_b32_e32 v88, 0xf149f2ca
	v_mov_b32_e32 v89, 0xf149f2ca
	v_mov_b32_e32 v90, 0xf149f2ca
	v_mov_b32_e32 v91, 0xf149f2ca
	v_mov_b32_e32 v92, 0xf149f2ca
	v_mov_b32_e32 v93, 0xf149f2ca
	v_mov_b32_e32 v94, 0xf149f2ca
	v_mov_b32_e32 v95, 0xf149f2ca
	v_mov_b32_e32 v225, 0
	v_mov_b32_e32 v166, 0
	v_mov_b32_e32 v175, 0
	v_mov_b32_e32 v202, 0
	s_waitcnt vmcnt(4)
	s_barrier
	ds_read_b128 v[112:115], v178
	ds_read_b128 v[116:119], v178 offset:32
	ds_read_b128 v[120:123], v178 offset:64
	ds_read_b128 v[124:127], v178 offset:96
	s_mov_b32 s16, 0
.Latt_loop:
	s_waitcnt lgkmcnt(3)
	v_mfma_f32_32x32x16_bf16 v[96:111], v[112:115], v[140:143], v[0:15]
	v_exp_f32_e32 v209, v80
	v_exp_f32_e32 v210, v81
	ds_read_b64_tr_b16 v[226:227], v198 offset:8448
	ds_read_b64_tr_b16 v[228:229], v198 offset:10560
	s_and_b32 s1, s35, 3
	s_cmp_lg_u32 s1, 0
	s_cbranch_scc1 .Latt_bt_0
	s_lshr_b32 s1, s35, 2
	s_lshl_b32 s2, s1, 14
	s_mov_b32 s3, 0
	s_lshl_b32 s4, s1, 8
	s_mov_b32 s5, 0
	v_lshl_add_u64 v[204:205], v[168:169], 0, s[2:3]
	v_lshl_add_u64 v[196:197], v[170:171], 0, s[4:5]
	v_cvt_pk_bf16_f32 v206, v182, v183
	global_load_dword v194, v[204:205], off
	global_load_dword v174, v[196:197], off
	global_store_dword v[204:205], v206, off
.Latt_bt_0:
	s_waitcnt lgkmcnt(4)
	v_mfma_f32_32x32x16_bf16 v[96:111], v[116:119], v[144:147], v[96:111]
	v_exp_f32_e32 v211, v82
	v_exp_f32_e32 v212, v83
	v_cvt_pk_bf16_f32 v156, v209, v210
	ds_read_b64_tr_b16 v[230:231], v199 offset:8448
	ds_read_b64_tr_b16 v[232:233], v199 offset:10560
	s_waitcnt lgkmcnt(5)
	v_mfma_f32_32x32x16_bf16 v[96:111], v[120:123], v[136:139], v[96:111]
	v_exp_f32_e32 v213, v84
	v_exp_f32_e32 v214, v85
	v_cvt_pk_bf16_f32 v157, v211, v212
	ds_read_b64_tr_b16 v[234:235], v201 offset:8448
	ds_read_b64_tr_b16 v[236:237], v201 offset:10560
	s_waitcnt lgkmcnt(6)
	v_mfma_f32_32x32x16_bf16 v[96:111], v[124:127], v[132:135], v[96:111]
	v_exp_f32_e32 v215, v86
	v_exp_f32_e32 v216, v87
	v_cvt_pk_bf16_f32 v158, v213, v214
	v_cvt_pk_bf16_f32 v159, v215, v216
	ds_read_b64_tr_b16 v[238:239], v203 offset:8448
	ds_read_b64_tr_b16 v[240:241], v203 offset:10560
	s_waitcnt lgkmcnt(6)
	v_mfma_f32_32x32x16_bf16 v[64:79], v[226:229], v[156:159], v[64:79]
	v_exp_f32_e32 v217, v88
	v_exp_f32_e32 v218, v89
	ds_read_b64_tr_b16 v[242:243], v198 offset:12672
	ds_read_b64_tr_b16 v[244:245], v198 offset:14784
	s_waitcnt lgkmcnt(6)
	v_mfma_f32_32x32x16_bf16 v[48:63], v[230:233], v[156:159], v[48:63]
	v_exp_f32_e32 v219, v90
	v_exp_f32_e32 v220, v91
	v_cvt_pk_bf16_f32 v160, v217, v218
	ds_read_b64_tr_b16 v[246:247], v199 offset:12672
	ds_read_b64_tr_b16 v[248:249], v199 offset:14784
	s_waitcnt lgkmcnt(6)
	v_mfma_f32_32x32x16_bf16 v[32:47], v[234:237], v[156:159], v[32:47]
	v_exp_f32_e32 v221, v92
	v_exp_f32_e32 v222, v93
	v_cvt_pk_bf16_f32 v161, v219, v220
	ds_read_b64_tr_b16 v[226:227], v201 offset:12672
	ds_read_b64_tr_b16 v[228:229], v201 offset:14784
	s_waitcnt lgkmcnt(6)
	v_mfma_f32_32x32x16_bf16 v[16:31], v[238:241], v[156:159], v[16:31]
	v_exp_f32_e32 v223, v94
	v_exp_f32_e32 v224, v95
	v_cvt_pk_bf16_f32 v162, v221, v222
	v_cvt_pk_bf16_f32 v163, v223, v224
	ds_read_b64_tr_b16 v[230:231], v203 offset:12672
	ds_read_b64_tr_b16 v[232:233], v203 offset:14784
	s_waitcnt lgkmcnt(6)
	v_mfma_f32_32x32x16_bf16 v[64:79], v[242:245], v[160:163], v[64:79]
	v_add_f32_e32 v225, v225, v209
	v_add_f32_e32 v166, v166, v210
	v_add_f32_e32 v175, v175, v211
	v_add_f32_e32 v202, v202, v212
	ds_read_b128 v[112:115], v178 offset:8448
	s_waitcnt lgkmcnt(5)
	v_mfma_f32_32x32x16_bf16 v[48:63], v[246:249], v[160:163], v[48:63]
	v_add_f32_e32 v225, v225, v213
	v_add_f32_e32 v166, v166, v214
	v_add_f32_e32 v175, v175, v215
	v_add_f32_e32 v202, v202, v216
	ds_read_b128 v[116:119], v178 offset:8480
	s_waitcnt lgkmcnt(4)
	v_mfma_f32_32x32x16_bf16 v[32:47], v[226:229], v[160:163], v[32:47]
	v_add_f32_e32 v225, v225, v217
	v_add_f32_e32 v166, v166, v218
	v_add_f32_e32 v175, v175, v219
	v_add_f32_e32 v202, v202, v220
	ds_read_b128 v[120:123], v178 offset:8512
	s_waitcnt lgkmcnt(3)
	v_mfma_f32_32x32x16_bf16 v[16:31], v[230:233], v[160:163], v[16:31]
	v_add_f32_e32 v225, v225, v221
	v_add_f32_e32 v166, v166, v222
	v_add_f32_e32 v175, v175, v223
	v_add_f32_e32 v202, v202, v224
	ds_read_b128 v[124:127], v178 offset:8544
	s_waitcnt lgkmcnt(3)
	v_mfma_f32_32x32x16_bf16 v[80:95], v[112:115], v[140:143], v[0:15]
	v_exp_f32_e32 v209, v96
	v_exp_f32_e32 v210, v97
	ds_read_b64_tr_b16 v[234:235], v184
	ds_read_b64_tr_b16 v[236:237], v184 offset:2112
	s_waitcnt lgkmcnt(4)
	v_mfma_f32_32x32x16_bf16 v[80:95], v[116:119], v[144:147], v[80:95]
	v_exp_f32_e32 v211, v98
	v_exp_f32_e32 v212, v99
	v_cvt_pk_bf16_f32 v148, v209, v210
	ds_read_b64_tr_b16 v[238:239], v185
	ds_read_b64_tr_b16 v[240:241], v185 offset:2112
	s_waitcnt lgkmcnt(5)
	v_mfma_f32_32x32x16_bf16 v[80:95], v[120:123], v[136:139], v[80:95]
	v_exp_f32_e32 v213, v100
	v_exp_f32_e32 v214, v101
	v_cvt_pk_bf16_f32 v149, v211, v212
	ds_read_b64_tr_b16 v[242:243], v186
	ds_read_b64_tr_b16 v[244:245], v186 offset:2112
	s_waitcnt lgkmcnt(6)
	v_mfma_f32_32x32x16_bf16 v[80:95], v[124:127], v[132:135], v[80:95]
	v_exp_f32_e32 v215, v102
	v_exp_f32_e32 v216, v103
	v_cvt_pk_bf16_f32 v150, v213, v214
	v_cvt_pk_bf16_f32 v151, v215, v216
	ds_read_b64_tr_b16 v[246:247], v187
	ds_read_b64_tr_b16 v[248:249], v187 offset:2112
	s_waitcnt lgkmcnt(6)
	v_mfma_f32_32x32x16_bf16 v[64:79], v[234:237], v[148:151], v[64:79]
	v_exp_f32_e32 v217, v104
	v_exp_f32_e32 v218, v105
	ds_read_b64_tr_b16 v[226:227], v184 offset:4224
	ds_read_b64_tr_b16 v[228:229], v184 offset:6336
	s_waitcnt lgkmcnt(6)
	v_mfma_f32_32x32x16_bf16 v[48:63], v[238:241], v[148:151], v[48:63]
	v_exp_f32_e32 v219, v106
	v_exp_f32_e32 v220, v107
	v_cvt_pk_bf16_f32 v152, v217, v218
	ds_read_b64_tr_b16 v[230:231], v185 offset:4224
	ds_read_b64_tr_b16 v[232:233], v185 offset:6336
	s_waitcnt lgkmcnt(6)
	v_mfma_f32_32x32x16_bf16 v[32:47], v[242:245], v[148:151], v[32:47]
	v_exp_f32_e32 v221, v108
	v_exp_f32_e32 v222, v109
	v_cvt_pk_bf16_f32 v153, v219, v220
	ds_read_b64_tr_b16 v[234:235], v186 offset:4224
	ds_read_b64_tr_b16 v[236:237], v186 offset:6336
	s_waitcnt lgkmcnt(6)
	v_mfma_f32_32x32x16_bf16 v[16:31], v[246:249], v[148:151], v[16:31]
	v_exp_f32_e32 v223, v110
	v_exp_f32_e32 v224, v111
	v_cvt_pk_bf16_f32 v154, v221, v222
	v_cvt_pk_bf16_f32 v155, v223, v224
	ds_read_b64_tr_b16 v[238:239], v187 offset:4224
	ds_read_b64_tr_b16 v[240:241], v187 offset:6336
	s_waitcnt lgkmcnt(6)
	v_mfma_f32_32x32x16_bf16 v[64:79], v[226:229], v[152:155], v[64:79]
	s_waitcnt vmcnt(0)
	s_barrier
	v_add_f32_e32 v225, v225, v209
	v_add_f32_e32 v166, v166, v210
	v_add_f32_e32 v175, v175, v211
	v_add_f32_e32 v202, v202, v212
	s_add_i32 m0, s17, 67584
	ds_read_b128 v[112:115], v178 offset:33792
	global_load_lds_dwordx4 v181, s[36:37]
	s_waitcnt lgkmcnt(5)
	v_mfma_f32_32x32x16_bf16 v[48:63], v[230:233], v[152:155], v[48:63]
	v_add_f32_e32 v225, v225, v213
	v_add_f32_e32 v166, v166, v214
	v_add_f32_e32 v175, v175, v215
	v_add_f32_e32 v202, v202, v216
	s_add_i32 m0, s17, 68640
	ds_read_b128 v[116:119], v178 offset:33824
	global_load_lds_dwordx4 v165, s[36:37]
	s_and_b32 s1, s35, 3
	s_add_i32 s35, s35, 1
	s_cmp_lg_u32 s1, 0
	s_cbranch_scc1 .Latt_bb_0
	v_lshlrev_b32_e32 v128, 16, v194
	v_and_b32_e32 v129, 0xffff0000, v194
	v_fma_f32 v182, v174, v182, v128
	v_fma_f32 v183, v174, v183, v129
.Latt_bb_0:
	s_waitcnt lgkmcnt(4)
	v_mfma_f32_32x32x16_bf16 v[32:47], v[234:237], v[152:155], v[32:47]
	v_add_f32_e32 v225, v225, v217
	v_add_f32_e32 v166, v166, v218
	v_add_f32_e32 v175, v175, v219
	v_add_f32_e32 v202, v202, v220
	s_add_i32 m0, s17, 84480
	ds_read_b128 v[120:123], v178 offset:33856
	global_load_lds_dwordx4 v207, s[36:37]
	s_waitcnt lgkmcnt(3)
	v_mfma_f32_32x32x16_bf16 v[16:31], v[238:241], v[152:155], v[16:31]
	v_add_f32_e32 v225, v225, v221
	v_add_f32_e32 v166, v166, v222
	v_add_f32_e32 v175, v175, v223
	v_add_f32_e32 v202, v202, v224
	s_add_i32 m0, s17, 85536
	ds_read_b128 v[124:127], v178 offset:33888
	global_load_lds_dwordx4 v208, s[36:37]
	s_add_u32 s36, s36, 0x68000
	s_addc_u32 s37, s37, 0
	s_cmp_eq_u32 s16, 1
	s_cselect_b32 s36, s38, s36
	s_cselect_b32 s37, s39, s37
	s_add_i32 s16, s16, 1
	s_waitcnt lgkmcnt(3)
	v_mfma_f32_32x32x16_bf16 v[96:111], v[112:115], v[140:143], v[0:15]
	v_exp_f32_e32 v209, v80
	v_exp_f32_e32 v210, v81
	ds_read_b64_tr_b16 v[242:243], v184 offset:8448
	ds_read_b64_tr_b16 v[244:245], v184 offset:10560
	s_and_b32 s1, s35, 3
	s_cmp_lg_u32 s1, 0
	s_cbranch_scc1 .Latt_bt_1
	s_lshr_b32 s1, s35, 2
	s_lshl_b32 s2, s1, 14
	s_mov_b32 s3, 0
	s_lshl_b32 s4, s1, 8
	s_mov_b32 s5, 0
	v_lshl_add_u64 v[204:205], v[168:169], 0, s[2:3]
	v_lshl_add_u64 v[196:197], v[170:171], 0, s[4:5]
	v_cvt_pk_bf16_f32 v206, v182, v183
	global_load_dword v194, v[204:205], off
	global_load_dword v174, v[196:197], off
	global_store_dword v[204:205], v206, off
.Latt_bt_1:
	s_waitcnt lgkmcnt(4)
	v_mfma_f32_32x32x16_bf16 v[96:111], v[116:119], v[144:147], v[96:111]
	v_exp_f32_e32 v211, v82
	v_exp_f32_e32 v212, v83
	v_cvt_pk_bf16_f32 v156, v209, v210
	ds_read_b64_tr_b16 v[246:247], v185 offset:8448
	ds_read_b64_tr_b16 v[248:249], v185 offset:10560
	s_waitcnt lgkmcnt(5)
	v_mfma_f32_32x32x16_bf16 v[96:111], v[120:123], v[136:139], v[96:111]
	v_exp_f32_e32 v213, v84
	v_exp_f32_e32 v214, v85
	v_cvt_pk_bf16_f32 v157, v211, v212
	ds_read_b64_tr_b16 v[226:227], v186 offset:8448
	ds_read_b64_tr_b16 v[228:229], v186 offset:10560
	s_waitcnt lgkmcnt(6)
	v_mfma_f32_32x32x16_bf16 v[96:111], v[124:127], v[132:135], v[96:111]
	v_exp_f32_e32 v215, v86
	v_exp_f32_e32 v216, v87
	v_cvt_pk_bf16_f32 v158, v213, v214
	v_cvt_pk_bf16_f32 v159, v215, v216
	ds_read_b64_tr_b16 v[230:231], v187 offset:8448
	ds_read_b64_tr_b16 v[232:233], v187 offset:10560
	s_waitcnt lgkmcnt(6)
	v_mfma_f32_32x32x16_bf16 v[64:79], v[242:245], v[156:159], v[64:79]
	v_exp_f32_e32 v217, v88
	v_exp_f32_e32 v218, v89
	ds_read_b64_tr_b16 v[234:235], v184 offset:12672
	ds_read_b64_tr_b16 v[236:237], v184 offset:14784
	s_waitcnt lgkmcnt(6)
	v_mfma_f32_32x32x16_bf16 v[48:63], v[246:249], v[156:159], v[48:63]
	v_exp_f32_e32 v219, v90
	v_exp_f32_e32 v220, v91
	v_cvt_pk_bf16_f32 v160, v217, v218
	ds_read_b64_tr_b16 v[238:239], v185 offset:12672
	ds_read_b64_tr_b16 v[240:241], v185 offset:14784
	s_waitcnt lgkmcnt(6)
	v_mfma_f32_32x32x16_bf16 v[32:47], v[226:229], v[156:159], v[32:47]
	v_exp_f32_e32 v221, v92
	v_exp_f32_e32 v222, v93
	v_cvt_pk_bf16_f32 v161, v219, v220
	ds_read_b64_tr_b16 v[242:243], v186 offset:12672
	ds_read_b64_tr_b16 v[244:245], v186 offset:14784
	s_waitcnt lgkmcnt(6)
	v_mfma_f32_32x32x16_bf16 v[16:31], v[230:233], v[156:159], v[16:31]
	v_exp_f32_e32 v223, v94
	v_exp_f32_e32 v224, v95
	v_cvt_pk_bf16_f32 v162, v221, v222
	v_cvt_pk_bf16_f32 v163, v223, v224
	ds_read_b64_tr_b16 v[246:247], v187 offset:12672
	ds_read_b64_tr_b16 v[248:249], v187 offset:14784
	s_waitcnt lgkmcnt(6)
	v_mfma_f32_32x32x16_bf16 v[64:79], v[234:237], v[160:163], v[64:79]
	v_add_f32_e32 v225, v225, v209
	v_add_f32_e32 v166, v166, v210
	v_add_f32_e32 v175, v175, v211
	v_add_f32_e32 v202, v202, v212
	ds_read_b128 v[112:115], v178 offset:42240
	s_waitcnt lgkmcnt(5)
	v_mfma_f32_32x32x16_bf16 v[48:63], v[238:241], v[160:163], v[48:63]
	v_add_f32_e32 v225, v225, v213
	v_add_f32_e32 v166, v166, v214
	v_add_f32_e32 v175, v175, v215
	v_add_f32_e32 v202, v202, v216
	ds_read_b128 v[116:119], v178 offset:42272
	s_waitcnt lgkmcnt(4)
	v_mfma_f32_32x32x16_bf16 v[32:47], v[242:245], v[160:163], v[32:47]
	v_add_f32_e32 v225, v225, v217
	v_add_f32_e32 v166, v166, v218
	v_add_f32_e32 v175, v175, v219
	v_add_f32_e32 v202, v202, v220
	ds_read_b128 v[120:123], v178 offset:42304
	s_waitcnt lgkmcnt(3)
	v_mfma_f32_32x32x16_bf16 v[16:31], v[246:249], v[160:163], v[16:31]
	v_add_f32_e32 v225, v225, v221
	v_add_f32_e32 v166, v166, v222
	v_add_f32_e32 v175, v175, v223
	v_add_f32_e32 v202, v202, v224
	ds_read_b128 v[124:127], v178 offset:42336
	s_waitcnt lgkmcnt(3)
	v_mfma_f32_32x32x16_bf16 v[80:95], v[112:115], v[140:143], v[0:15]
	v_exp_f32_e32 v209, v96
	v_exp_f32_e32 v210, v97
	ds_read_b64_tr_b16 v[226:227], v184 offset:33792
	ds_read_b64_tr_b16 v[228:229], v184 offset:35904
	s_waitcnt lgkmcnt(4)
	v_mfma_f32_32x32x16_bf16 v[80:95], v[116:119], v[144:147], v[80:95]
	v_exp_f32_e32 v211, v98
	v_exp_f32_e32 v212, v99
	v_cvt_pk_bf16_f32 v148, v209, v210
	ds_read_b64_tr_b16 v[230:231], v185 offset:33792
	ds_read_b64_tr_b16 v[232:233], v185 offset:35904
	s_waitcnt lgkmcnt(5)
	v_mfma_f32_32x32x16_bf16 v[80:95], v[120:123], v[136:139], v[80:95]
	v_exp_f32_e32 v213, v100
	v_exp_f32_e32 v214, v101
	v_cvt_pk_bf16_f32 v149, v211, v212
	ds_read_b64_tr_b16 v[234:235], v186 offset:33792
	ds_read_b64_tr_b16 v[236:237], v186 offset:35904
	s_waitcnt lgkmcnt(6)
	v_mfma_f32_32x32x16_bf16 v[80:95], v[124:127], v[132:135], v[80:95]
	v_exp_f32_e32 v215, v102
	v_exp_f32_e32 v216, v103
	v_cvt_pk_bf16_f32 v150, v213, v214
	v_cvt_pk_bf16_f32 v151, v215, v216
	ds_read_b64_tr_b16 v[238:239], v187 offset:33792
	ds_read_b64_tr_b16 v[240:241], v187 offset:35904
	s_waitcnt lgkmcnt(6)
	v_mfma_f32_32x32x16_bf16 v[64:79], v[226:229], v[148:151], v[64:79]
	v_exp_f32_e32 v217, v104
	v_exp_f32_e32 v218, v105
	ds_read_b64_tr_b16 v[242:243], v184 offset:38016
	ds_read_b64_tr_b16 v[244:245], v184 offset:40128
	s_waitcnt lgkmcnt(6)
	v_mfma_f32_32x32x16_bf16 v[48:63], v[230:233], v[148:151], v[48:63]
	v_exp_f32_e32 v219, v106
	v_exp_f32_e32 v220, v107
	v_cvt_pk_bf16_f32 v152, v217, v218
	ds_read_b64_tr_b16 v[246:247], v185 offset:38016
	ds_read_b64_tr_b16 v[248:249], v185 offset:40128
	s_waitcnt lgkmcnt(6)
	v_mfma_f32_32x32x16_bf16 v[32:47], v[234:237], v[148:151], v[32:47]
	v_exp_f32_e32 v221, v108
	v_exp_f32_e32 v222, v109
	v_cvt_pk_bf16_f32 v153, v219, v220
	ds_read_b64_tr_b16 v[226:227], v186 offset:38016
	ds_read_b64_tr_b16 v[228:229], v186 offset:40128
	s_waitcnt lgkmcnt(6)
	v_mfma_f32_32x32x16_bf16 v[16:31], v[238:241], v[148:151], v[16:31]
	v_exp_f32_e32 v223, v110
	v_exp_f32_e32 v224, v111
	v_cvt_pk_bf16_f32 v154, v221, v222
	v_cvt_pk_bf16_f32 v155, v223, v224
	ds_read_b64_tr_b16 v[230:231], v187 offset:38016
	ds_read_b64_tr_b16 v[232:233], v187 offset:40128
	s_waitcnt lgkmcnt(6)
	v_mfma_f32_32x32x16_bf16 v[64:79], v[242:245], v[152:155], v[64:79]
	s_waitcnt vmcnt(0)
	s_barrier
	v_add_f32_e32 v225, v225, v209
	v_add_f32_e32 v166, v166, v210
	v_add_f32_e32 v175, v175, v211
	v_add_f32_e32 v202, v202, v212
	s_add_i32 m0, s17, 0
	ds_read_b128 v[112:115], v180
	global_load_lds_dwordx4 v181, s[36:37]
	s_waitcnt lgkmcnt(5)
	v_mfma_f32_32x32x16_bf16 v[48:63], v[246:249], v[152:155], v[48:63]
	v_add_f32_e32 v225, v225, v213
	v_add_f32_e32 v166, v166, v214
	v_add_f32_e32 v175, v175, v215
	v_add_f32_e32 v202, v202, v216
	s_add_i32 m0, s17, 1056
	ds_read_b128 v[116:119], v180 offset:32
	global_load_lds_dwordx4 v165, s[36:37]
	s_and_b32 s1, s35, 3
	s_add_i32 s35, s35, 1
	s_cmp_lg_u32 s1, 0
	s_cbranch_scc1 .Latt_bb_1
	v_lshlrev_b32_e32 v128, 16, v194
	v_and_b32_e32 v129, 0xffff0000, v194
	v_fma_f32 v182, v174, v182, v128
	v_fma_f32 v183, v174, v183, v129
.Latt_bb_1:
	s_waitcnt lgkmcnt(4)
	v_mfma_f32_32x32x16_bf16 v[32:47], v[226:229], v[152:155], v[32:47]
	v_add_f32_e32 v225, v225, v217
	v_add_f32_e32 v166, v166, v218
	v_add_f32_e32 v175, v175, v219
	v_add_f32_e32 v202, v202, v220
	s_add_i32 m0, s17, 16896
	ds_read_b128 v[120:123], v180 offset:64
	global_load_lds_dwordx4 v207, s[36:37]
	s_waitcnt lgkmcnt(3)
	v_mfma_f32_32x32x16_bf16 v[16:31], v[230:233], v[152:155], v[16:31]
	v_add_f32_e32 v225, v225, v221
	v_add_f32_e32 v166, v166, v222
	v_add_f32_e32 v175, v175, v223
	v_add_f32_e32 v202, v202, v224
	s_add_i32 m0, s17, 17952
	ds_read_b128 v[124:127], v180 offset:96
	global_load_lds_dwordx4 v208, s[36:37]
	s_add_u32 s36, s36, 0x68000
	s_addc_u32 s37, s37, 0
	s_cmp_eq_u32 s16, 1
	s_cselect_b32 s36, s38, s36
	s_cselect_b32 s37, s39, s37
	s_add_i32 s16, s16, 1
	s_waitcnt lgkmcnt(3)
	v_mfma_f32_32x32x16_bf16 v[96:111], v[112:115], v[140:143], v[0:15]
	v_exp_f32_e32 v209, v80
	v_exp_f32_e32 v210, v81
	ds_read_b64_tr_b16 v[234:235], v184 offset:42240
	ds_read_b64_tr_b16 v[236:237], v184 offset:44352
	s_and_b32 s1, s35, 3
	s_cmp_lg_u32 s1, 0
	s_cbranch_scc1 .Latt_bt_2
	s_lshr_b32 s1, s35, 2
	s_lshl_b32 s2, s1, 14
	s_mov_b32 s3, 0
	s_lshl_b32 s4, s1, 8
	s_mov_b32 s5, 0
	v_lshl_add_u64 v[204:205], v[168:169], 0, s[2:3]
	v_lshl_add_u64 v[196:197], v[170:171], 0, s[4:5]
	v_cvt_pk_bf16_f32 v206, v182, v183
	global_load_dword v194, v[204:205], off
	global_load_dword v174, v[196:197], off
	global_store_dword v[204:205], v206, off
.Latt_bt_2:
	s_waitcnt lgkmcnt(4)
	v_mfma_f32_32x32x16_bf16 v[96:111], v[116:119], v[144:147], v[96:111]
	v_exp_f32_e32 v211, v82
	v_exp_f32_e32 v212, v83
	v_cvt_pk_bf16_f32 v156, v209, v210
	ds_read_b64_tr_b16 v[238:239], v185 offset:42240
	ds_read_b64_tr_b16 v[240:241], v185 offset:44352
	s_waitcnt lgkmcnt(5)
	v_mfma_f32_32x32x16_bf16 v[96:111], v[120:123], v[136:139], v[96:111]
	v_exp_f32_e32 v213, v84
	v_exp_f32_e32 v214, v85
	v_cvt_pk_bf16_f32 v157, v211, v212
	ds_read_b64_tr_b16 v[242:243], v186 offset:42240
	ds_read_b64_tr_b16 v[244:245], v186 offset:44352
	s_waitcnt lgkmcnt(6)
	v_mfma_f32_32x32x16_bf16 v[96:111], v[124:127], v[132:135], v[96:111]
	v_exp_f32_e32 v215, v86
	v_exp_f32_e32 v216, v87
	v_cvt_pk_bf16_f32 v158, v213, v214
	v_cvt_pk_bf16_f32 v159, v215, v216
	ds_read_b64_tr_b16 v[246:247], v187 offset:42240
	ds_read_b64_tr_b16 v[248:249], v187 offset:44352
	s_waitcnt lgkmcnt(6)
	v_mfma_f32_32x32x16_bf16 v[64:79], v[234:237], v[156:159], v[64:79]
	v_exp_f32_e32 v217, v88
	v_exp_f32_e32 v218, v89
	ds_read_b64_tr_b16 v[226:227], v184 offset:46464
	ds_read_b64_tr_b16 v[228:229], v184 offset:48576
	s_waitcnt lgkmcnt(6)
	v_mfma_f32_32x32x16_bf16 v[48:63], v[238:241], v[156:159], v[48:63]
	v_exp_f32_e32 v219, v90
	v_exp_f32_e32 v220, v91
	v_cvt_pk_bf16_f32 v160, v217, v218
	ds_read_b64_tr_b16 v[230:231], v185 offset:46464
	ds_read_b64_tr_b16 v[232:233], v185 offset:48576
	s_waitcnt lgkmcnt(6)
	v_mfma_f32_32x32x16_bf16 v[32:47], v[242:245], v[156:159], v[32:47]
	v_exp_f32_e32 v221, v92
	v_exp_f32_e32 v222, v93
	v_cvt_pk_bf16_f32 v161, v219, v220
	ds_read_b64_tr_b16 v[234:235], v186 offset:46464
	ds_read_b64_tr_b16 v[236:237], v186 offset:48576
	s_waitcnt lgkmcnt(6)
	v_mfma_f32_32x32x16_bf16 v[16:31], v[246:249], v[156:159], v[16:31]
	v_exp_f32_e32 v223, v94
	v_exp_f32_e32 v224, v95
	v_cvt_pk_bf16_f32 v162, v221, v222
	v_cvt_pk_bf16_f32 v163, v223, v224
	ds_read_b64_tr_b16 v[238:239], v187 offset:46464
	ds_read_b64_tr_b16 v[240:241], v187 offset:48576
	s_waitcnt lgkmcnt(6)
	v_mfma_f32_32x32x16_bf16 v[64:79], v[226:229], v[160:163], v[64:79]
	v_add_f32_e32 v225, v225, v209
	v_add_f32_e32 v166, v166, v210
	v_add_f32_e32 v175, v175, v211
	v_add_f32_e32 v202, v202, v212
	ds_read_b128 v[112:115], v180 offset:8448
	s_waitcnt lgkmcnt(5)
	v_mfma_f32_32x32x16_bf16 v[48:63], v[230:233], v[160:163], v[48:63]
	v_add_f32_e32 v225, v225, v213
	v_add_f32_e32 v166, v166, v214
	v_add_f32_e32 v175, v175, v215
	v_add_f32_e32 v202, v202, v216
	ds_read_b128 v[116:119], v180 offset:8480
	s_waitcnt lgkmcnt(4)
	v_mfma_f32_32x32x16_bf16 v[32:47], v[234:237], v[160:163], v[32:47]
	v_add_f32_e32 v225, v225, v217
	v_add_f32_e32 v166, v166, v218
	v_add_f32_e32 v175, v175, v219
	v_add_f32_e32 v202, v202, v220
	ds_read_b128 v[120:123], v180 offset:8512
	s_waitcnt lgkmcnt(3)
	v_mfma_f32_32x32x16_bf16 v[16:31], v[238:241], v[160:163], v[16:31]
	v_add_f32_e32 v225, v225, v221
	v_add_f32_e32 v166, v166, v222
	v_add_f32_e32 v175, v175, v223
	v_add_f32_e32 v202, v202, v224
	ds_read_b128 v[124:127], v180 offset:8544
	s_waitcnt lgkmcnt(3)
	v_mfma_f32_32x32x16_bf16 v[80:95], v[112:115], v[140:143], v[0:15]
	v_exp_f32_e32 v209, v96
	v_exp_f32_e32 v210, v97
	ds_read_b64_tr_b16 v[242:243], v198
	ds_read_b64_tr_b16 v[244:245], v198 offset:2112
	s_waitcnt lgkmcnt(4)
	v_mfma_f32_32x32x16_bf16 v[80:95], v[116:119], v[144:147], v[80:95]
	v_exp_f32_e32 v211, v98
	v_exp_f32_e32 v212, v99
	v_cvt_pk_bf16_f32 v148, v209, v210
	ds_read_b64_tr_b16 v[246:247], v199
	ds_read_b64_tr_b16 v[248:249], v199 offset:2112
	s_waitcnt lgkmcnt(5)
	v_mfma_f32_32x32x16_bf16 v[80:95], v[120:123], v[136:139], v[80:95]
	v_exp_f32_e32 v213, v100
	v_exp_f32_e32 v214, v101
	v_cvt_pk_bf16_f32 v149, v211, v212
	ds_read_b64_tr_b16 v[226:227], v201
	ds_read_b64_tr_b16 v[228:229], v201 offset:2112
	s_waitcnt lgkmcnt(6)
	v_mfma_f32_32x32x16_bf16 v[80:95], v[124:127], v[132:135], v[80:95]
	v_exp_f32_e32 v215, v102
	v_exp_f32_e32 v216, v103
	v_cvt_pk_bf16_f32 v150, v213, v214
	v_cvt_pk_bf16_f32 v151, v215, v216
	ds_read_b64_tr_b16 v[230:231], v203
	ds_read_b64_tr_b16 v[232:233], v203 offset:2112
	s_waitcnt lgkmcnt(6)
	v_mfma_f32_32x32x16_bf16 v[64:79], v[242:245], v[148:151], v[64:79]
	v_exp_f32_e32 v217, v104
	v_exp_f32_e32 v218, v105
	ds_read_b64_tr_b16 v[234:235], v198 offset:4224
	ds_read_b64_tr_b16 v[236:237], v198 offset:6336
	s_waitcnt lgkmcnt(6)
	v_mfma_f32_32x32x16_bf16 v[48:63], v[246:249], v[148:151], v[48:63]
	v_exp_f32_e32 v219, v106
	v_exp_f32_e32 v220, v107
	v_cvt_pk_bf16_f32 v152, v217, v218
	ds_read_b64_tr_b16 v[238:239], v199 offset:4224
	ds_read_b64_tr_b16 v[240:241], v199 offset:6336
	s_waitcnt lgkmcnt(6)
	v_mfma_f32_32x32x16_bf16 v[32:47], v[226:229], v[148:151], v[32:47]
	v_exp_f32_e32 v221, v108
	v_exp_f32_e32 v222, v109
	v_cvt_pk_bf16_f32 v153, v219, v220
	ds_read_b64_tr_b16 v[242:243], v201 offset:4224
	ds_read_b64_tr_b16 v[244:245], v201 offset:6336
	s_waitcnt lgkmcnt(6)
	v_mfma_f32_32x32x16_bf16 v[16:31], v[230:233], v[148:151], v[16:31]
	v_exp_f32_e32 v223, v110
	v_exp_f32_e32 v224, v111
	v_cvt_pk_bf16_f32 v154, v221, v222
	v_cvt_pk_bf16_f32 v155, v223, v224
	ds_read_b64_tr_b16 v[246:247], v203 offset:4224
	ds_read_b64_tr_b16 v[248:249], v203 offset:6336
	s_waitcnt lgkmcnt(6)
	v_mfma_f32_32x32x16_bf16 v[64:79], v[234:237], v[152:155], v[64:79]
	s_waitcnt vmcnt(0)
	s_barrier
	v_add_f32_e32 v225, v225, v209
	v_add_f32_e32 v166, v166, v210
	v_add_f32_e32 v175, v175, v211
	v_add_f32_e32 v202, v202, v212
	s_add_i32 m0, s17, 33792
	ds_read_b128 v[112:115], v178
	global_load_lds_dwordx4 v181, s[36:37]
	s_waitcnt lgkmcnt(5)
	v_mfma_f32_32x32x16_bf16 v[48:63], v[238:241], v[152:155], v[48:63]
	v_add_f32_e32 v225, v225, v213
	v_add_f32_e32 v166, v166, v214
	v_add_f32_e32 v175, v175, v215
	v_add_f32_e32 v202, v202, v216
	s_add_i32 m0, s17, 34848
	ds_read_b128 v[116:119], v178 offset:32
	global_load_lds_dwordx4 v165, s[36:37]
	s_and_b32 s1, s35, 3
	s_add_i32 s35, s35, 1
	s_cmp_lg_u32 s1, 0
	s_cbranch_scc1 .Latt_bb_2
	v_lshlrev_b32_e32 v128, 16, v194
	v_and_b32_e32 v129, 0xffff0000, v194
	v_fma_f32 v182, v174, v182, v128
	v_fma_f32 v183, v174, v183, v129
.Latt_bb_2:
	s_waitcnt lgkmcnt(4)
	v_mfma_f32_32x32x16_bf16 v[32:47], v[242:245], v[152:155], v[32:47]
	v_add_f32_e32 v225, v225, v217
	v_add_f32_e32 v166, v166, v218
	v_add_f32_e32 v175, v175, v219
	v_add_f32_e32 v202, v202, v220
	s_add_i32 m0, s17, 50688
	ds_read_b128 v[120:123], v178 offset:64
	global_load_lds_dwordx4 v207, s[36:37]
	s_waitcnt lgkmcnt(3)
	v_mfma_f32_32x32x16_bf16 v[16:31], v[246:249], v[152:155], v[16:31]
	v_add_f32_e32 v225, v225, v221
	v_add_f32_e32 v166, v166, v222
	v_add_f32_e32 v175, v175, v223
	v_add_f32_e32 v202, v202, v224
	s_add_i32 m0, s17, 51744
	ds_read_b128 v[124:127], v178 offset:96
	global_load_lds_dwordx4 v208, s[36:37]
	s_add_u32 s36, s36, 0x68000
	s_addc_u32 s37, s37, 0
	s_cmp_eq_u32 s16, 1
	s_cselect_b32 s36, s38, s36
	s_cselect_b32 s37, s39, s37
	s_add_i32 s16, s16, 1
	s_cmpk_lt_u32 s16, 0x84
	s_cbranch_scc1 .Latt_loop
	ds_read_b64_tr_b16 v[226:227], v198 offset:8448
	ds_read_b64_tr_b16 v[228:229], v198 offset:10560
	ds_read_b64_tr_b16 v[230:231], v199 offset:8448
	ds_read_b64_tr_b16 v[232:233], v199 offset:10560
	ds_read_b64_tr_b16 v[234:235], v201 offset:8448
	ds_read_b64_tr_b16 v[236:237], v201 offset:10560
	ds_read_b64_tr_b16 v[238:239], v203 offset:8448
	ds_read_b64_tr_b16 v[240:241], v203 offset:10560
	ds_read_b64_tr_b16 v[242:243], v198 offset:12672
	ds_read_b64_tr_b16 v[244:245], v198 offset:14784
	ds_read_b64_tr_b16 v[246:247], v199 offset:12672
	ds_read_b64_tr_b16 v[248:249], v199 offset:14784
	ds_read_b64_tr_b16 v[112:113], v201 offset:12672
	ds_read_b64_tr_b16 v[114:115], v201 offset:14784
	ds_read_b64_tr_b16 v[120:121], v203 offset:12672
	ds_read_b64_tr_b16 v[122:123], v203 offset:14784
	v_exp_f32_e32 v209, v80
	v_exp_f32_e32 v210, v81
	v_exp_f32_e32 v211, v82
	v_exp_f32_e32 v212, v83
	v_exp_f32_e32 v213, v84
	v_exp_f32_e32 v214, v85
	v_exp_f32_e32 v215, v86
	v_exp_f32_e32 v216, v87
	v_exp_f32_e32 v217, v88
	v_exp_f32_e32 v218, v89
	v_exp_f32_e32 v219, v90
	v_exp_f32_e32 v220, v91
	v_exp_f32_e32 v221, v92
	v_exp_f32_e32 v222, v93
	v_exp_f32_e32 v223, v94
	v_exp_f32_e32 v224, v95
	s_nop 0
	v_cvt_pk_bf16_f32 v156, v209, v210
	v_cvt_pk_bf16_f32 v157, v211, v212
	v_cvt_pk_bf16_f32 v158, v213, v214
	v_cvt_pk_bf16_f32 v159, v215, v216
	v_cvt_pk_bf16_f32 v160, v217, v218
	v_cvt_pk_bf16_f32 v161, v219, v220
	v_cvt_pk_bf16_f32 v162, v221, v222
	v_cvt_pk_bf16_f32 v163, v223, v224
	v_add_f32_e32 v225, v225, v209
	v_add_f32_e32 v166, v166, v210
	v_add_f32_e32 v175, v175, v211
	v_add_f32_e32 v202, v202, v212
	v_add_f32_e32 v225, v225, v213
	v_add_f32_e32 v166, v166, v214
	v_add_f32_e32 v175, v175, v215
	v_add_f32_e32 v202, v202, v216
	v_add_f32_e32 v225, v225, v217
	v_add_f32_e32 v166, v166, v218
	v_add_f32_e32 v175, v175, v219
	v_add_f32_e32 v202, v202, v220
	v_add_f32_e32 v225, v225, v221
	v_add_f32_e32 v166, v166, v222
	v_add_f32_e32 v175, v175, v223
	v_add_f32_e32 v202, v202, v224
	s_waitcnt lgkmcnt(0)
	v_mfma_f32_32x32x16_bf16 v[64:79], v[226:229], v[156:159], v[64:79]
	v_mfma_f32_32x32x16_bf16 v[48:63], v[230:233], v[156:159], v[48:63]
	v_mfma_f32_32x32x16_bf16 v[32:47], v[234:237], v[156:159], v[32:47]
	v_mfma_f32_32x32x16_bf16 v[16:31], v[238:241], v[156:159], v[16:31]
	v_mfma_f32_32x32x16_bf16 v[64:79], v[242:245], v[160:163], v[64:79]
	v_mfma_f32_32x32x16_bf16 v[48:63], v[246:249], v[160:163], v[48:63]
	v_mfma_f32_32x32x16_bf16 v[32:47], v[112:115], v[160:163], v[32:47]
	v_mfma_f32_32x32x16_bf16 v[16:31], v[120:123], v[160:163], v[16:31]
	v_add_f32_e32 v225, v225, v166
	v_add_f32_e32 v175, v175, v202
	v_add_f32_e32 v80, v225, v175
	v_and_b32_e32 v196, 63, v188
	s_cmpk_lt_u32 s34, 0x100
	s_cselect_b64 s[4:5], -1, 0
	s_lshl_b32 s0, s31, 14
	s_waitcnt vmcnt(0)
	s_barrier
	ds_bpermute_b32 v81, v195, v80
	s_nop 7
	s_nop 7
	s_cmp_eq_u32 s30, 1
	s_waitcnt lgkmcnt(0)
	v_add_f32_e32 v80, v80, v81
	v_cndmask_b32_e64 v81, v164, 1.0, s[4:5]
	v_div_scale_f32 v82, s[16:17], v80, v80, v81
	v_rcp_f32_e32 v83, v82
	s_nop 0
	v_fma_f32 v84, -v82, v83, 1.0
	v_fmac_f32_e32 v83, v84, v83
	v_div_scale_f32 v84, vcc, v81, v80, v81
	v_mul_f32_e32 v85, v84, v83
	v_fma_f32 v86, -v82, v85, v84
	v_fmac_f32_e32 v85, v86, v83
	v_fma_f32 v82, -v82, v85, v84
	v_div_fmas_f32 v82, v82, v83, v85
	v_div_fixup_f32 v92, v82, v80, v81
	v_pk_mul_f32 v[88:89], v[64:65], v[92:93] op_sel_hi:[1,0]
	v_pk_mul_f32 v[90:91], v[66:67], v[92:93] op_sel_hi:[1,0]
	v_pk_mul_f32 v[82:83], v[68:69], v[92:93] op_sel_hi:[1,0]
	v_pk_mul_f32 v[86:87], v[70:71], v[92:93] op_sel_hi:[1,0]
	v_pk_mul_f32 v[80:81], v[72:73], v[92:93] op_sel_hi:[1,0]
	v_pk_mul_f32 v[84:85], v[74:75], v[92:93] op_sel_hi:[1,0]
	v_pk_mul_f32 v[72:73], v[76:77], v[92:93] op_sel_hi:[1,0]
	v_pk_mul_f32 v[78:79], v[78:79], v[92:93] op_sel_hi:[1,0]
	v_pk_mul_f32 v[68:69], v[48:49], v[92:93] op_sel_hi:[1,0]
	v_pk_mul_f32 v[76:77], v[50:51], v[92:93] op_sel_hi:[1,0]
	v_pk_mul_f32 v[66:67], v[52:53], v[92:93] op_sel_hi:[1,0]
	v_pk_mul_f32 v[74:75], v[54:55], v[92:93] op_sel_hi:[1,0]
	v_pk_mul_f32 v[64:65], v[56:57], v[92:93] op_sel_hi:[1,0]
	v_pk_mul_f32 v[70:71], v[58:59], v[92:93] op_sel_hi:[1,0]
	v_pk_mul_f32 v[54:55], v[60:61], v[92:93] op_sel_hi:[1,0]
	v_pk_mul_f32 v[60:61], v[62:63], v[92:93] op_sel_hi:[1,0]
	v_pk_mul_f32 v[50:51], v[32:33], v[92:93] op_sel_hi:[1,0]
	v_pk_mul_f32 v[58:59], v[34:35], v[92:93] op_sel_hi:[1,0]
	v_pk_mul_f32 v[48:49], v[36:37], v[92:93] op_sel_hi:[1,0]
	v_pk_mul_f32 v[56:57], v[38:39], v[92:93] op_sel_hi:[1,0]
	v_pk_mul_f32 v[40:41], v[40:41], v[92:93] op_sel_hi:[1,0]
	v_pk_mul_f32 v[52:53], v[42:43], v[92:93] op_sel_hi:[1,0]
	v_pk_mul_f32 v[36:37], v[44:45], v[92:93] op_sel_hi:[1,0]
	v_pk_mul_f32 v[44:45], v[46:47], v[92:93] op_sel_hi:[1,0]
	v_pk_mul_f32 v[34:35], v[16:17], v[92:93] op_sel_hi:[1,0]
	v_pk_mul_f32 v[42:43], v[18:19], v[92:93] op_sel_hi:[1,0]
	v_pk_mul_f32 v[32:33], v[20:21], v[92:93] op_sel_hi:[1,0]
	v_pk_mul_f32 v[38:39], v[22:23], v[92:93] op_sel_hi:[1,0]
	v_pk_mul_f32 v[20:21], v[24:25], v[92:93] op_sel_hi:[1,0]
	v_pk_mul_f32 v[22:23], v[26:27], v[92:93] op_sel_hi:[1,0]
	v_pk_mul_f32 v[16:17], v[28:29], v[92:93] op_sel_hi:[1,0]
	v_pk_mul_f32 v[18:19], v[30:31], v[92:93] op_sel_hi:[1,0]
	v_lshl_add_u32 v24, v196, 2, s0
	s_cbranch_scc0 .LBB0_446
	ds_write2st64_b32 v24, v88, v89 offset1:1
	ds_write2st64_b32 v24, v90, v91 offset0:2 offset1:3
	ds_write2st64_b32 v24, v82, v83 offset0:4 offset1:5
	ds_write2st64_b32 v24, v86, v87 offset0:6 offset1:7
	ds_write2st64_b32 v24, v80, v81 offset0:8 offset1:9
	ds_write2st64_b32 v24, v84, v85 offset0:10 offset1:11
	ds_write2st64_b32 v24, v72, v73 offset0:12 offset1:13
	ds_write2st64_b32 v24, v78, v79 offset0:14 offset1:15
	ds_write2st64_b32 v24, v68, v69 offset0:16 offset1:17
	ds_write2st64_b32 v24, v76, v77 offset0:18 offset1:19
	ds_write2st64_b32 v24, v66, v67 offset0:20 offset1:21
	ds_write2st64_b32 v24, v74, v75 offset0:22 offset1:23
	ds_write2st64_b32 v24, v64, v65 offset0:24 offset1:25
	ds_write2st64_b32 v24, v70, v71 offset0:26 offset1:27
	ds_write2st64_b32 v24, v54, v55 offset0:28 offset1:29
	ds_write2st64_b32 v24, v60, v61 offset0:30 offset1:31
	ds_write2st64_b32 v24, v50, v51 offset0:32 offset1:33
	ds_write2st64_b32 v24, v58, v59 offset0:34 offset1:35
	ds_write2st64_b32 v24, v48, v49 offset0:36 offset1:37
	ds_write2st64_b32 v24, v56, v57 offset0:38 offset1:39
	ds_write2st64_b32 v24, v40, v41 offset0:40 offset1:41
	ds_write2st64_b32 v24, v52, v53 offset0:42 offset1:43
	ds_write2st64_b32 v24, v36, v37 offset0:44 offset1:45
	ds_write2st64_b32 v24, v44, v45 offset0:46 offset1:47
	ds_write2st64_b32 v24, v34, v35 offset0:48 offset1:49
	ds_write2st64_b32 v24, v42, v43 offset0:50 offset1:51
	ds_write2st64_b32 v24, v32, v33 offset0:52 offset1:53
	ds_write2st64_b32 v24, v38, v39 offset0:54 offset1:55
	ds_write2st64_b32 v24, v20, v21 offset0:56 offset1:57
	ds_write2st64_b32 v24, v22, v23 offset0:58 offset1:59
	ds_write2st64_b32 v24, v16, v17 offset0:60 offset1:61
	ds_write2st64_b32 v24, v18, v19 offset0:62 offset1:63
